# write-through (sc1) dwordx4 stores also in the prologue weight copies, final norm and K/V gather
# baseline (speedup 1.0000x reference)
.LBB0_1409:
	s_andn2_b64 vcc, exec, s[30:31]
	v_lshl_add_u64 v[110:111], v[88:89], 0, s[8:9]
	s_cbranch_vccnz .LBB0_1411
	global_store_dwordx4 v[110:111], v[78:81], off sc1

.LBB0_1413:
	s_andn2_b64 vcc, exec, s[8:9]
	s_cbranch_vccnz .LBB0_1415
	global_store_dwordx4 v[110:111], v[74:77], off offset:1024 sc1

.LBB0_1417:
	s_andn2_b64 vcc, exec, s[8:9]
	s_cbranch_vccnz .LBB0_1419
	global_store_dwordx4 v[110:111], v[70:73], off offset:2048 sc1

.LBB0_1421:
	s_andn2_b64 vcc, exec, s[8:9]
	s_cbranch_vccnz .LBB0_1423
	global_store_dwordx4 v[110:111], v[66:69], off offset:3072 sc1

.LBB0_1425:
	s_andn2_b64 vcc, exec, s[8:9]
	v_lshl_add_u64 v[68:69], v[88:89], 0, s[24:25]
	s_cbranch_vccnz .LBB0_1427
	global_store_dwordx4 v[68:69], v[62:65], off sc1

.LBB0_1429:
	s_andn2_b64 vcc, exec, s[8:9]
	s_cbranch_vccnz .LBB0_1431
	global_store_dwordx4 v[68:69], v[58:61], off offset:1024 sc1

.LBB0_1433:
	s_andn2_b64 vcc, exec, s[8:9]
	s_cbranch_vccnz .LBB0_1435
	global_store_dwordx4 v[68:69], v[54:57], off offset:2048 sc1

.LBB0_1437:
	s_andn2_b64 vcc, exec, s[8:9]
	s_cbranch_vccnz .LBB0_1439
	global_store_dwordx4 v[68:69], v[50:53], off offset:3072 sc1

.LBB0_1441:
	s_andn2_b64 vcc, exec, s[8:9]
	v_lshl_add_u64 v[52:53], v[88:89], 0, s[20:21]
	s_cbranch_vccnz .LBB0_1443
	global_store_dwordx4 v[52:53], v[46:49], off sc1

.LBB0_1445:
	s_andn2_b64 vcc, exec, s[8:9]
	s_cbranch_vccnz .LBB0_1447
	global_store_dwordx4 v[52:53], v[42:45], off offset:1024 sc1

.LBB0_1449:
	s_andn2_b64 vcc, exec, s[8:9]
	s_cbranch_vccnz .LBB0_1451
	global_store_dwordx4 v[52:53], v[38:41], off offset:2048 sc1

.LBB0_1453:
	s_andn2_b64 vcc, exec, s[8:9]
	s_cbranch_vccnz .LBB0_1455
	global_store_dwordx4 v[52:53], v[34:37], off offset:3072 sc1

.LBB0_1457:
	s_andn2_b64 vcc, exec, s[8:9]
	v_lshl_add_u64 v[36:37], v[88:89], 0, s[16:17]
	s_cbranch_vccnz .LBB0_1459
	global_store_dwordx4 v[36:37], v[30:33], off sc1

.LBB0_1461:
	s_andn2_b64 vcc, exec, s[8:9]
	s_cbranch_vccnz .LBB0_1463
	global_store_dwordx4 v[36:37], v[26:29], off offset:1024 sc1

.LBB0_1465:
	s_andn2_b64 vcc, exec, s[8:9]
	s_cbranch_vccnz .LBB0_1467
	global_store_dwordx4 v[36:37], v[22:25], off offset:2048 sc1

.LBB0_1470:
	global_store_dwordx4 v[36:37], v[18:21], off offset:3072 sc1
	s_branch .LBB0_1406

.LBB0_1477:
	s_or_b64 exec, exec, s[12:13]
	v_add_u32_e32 v2, 0x400, v11
	s_waitcnt vmcnt(0)
	ds_write2_b32 v11, v13, v14 offset1:66
	ds_write2_b32 v11, v16, v15 offset0:132 offset1:198
	ds_write2_b32 v2, v18, v17 offset0:8 offset1:74
	ds_write2_b32 v2, v20, v19 offset0:140 offset1:206
	v_add_u32_e32 v2, 0x800, v11
	ds_write2_b32 v2, v22, v21 offset0:16 offset1:82
	ds_write2_b32 v2, v24, v23 offset0:148 offset1:214
	v_add_u32_e32 v2, 0xc00, v11
	ds_write2_b32 v2, v26, v25 offset0:24 offset1:90
	ds_write2_b32 v2, v28, v27 offset0:156 offset1:222
	v_add_u32_e32 v2, 0x1000, v11
	ds_write2_b32 v2, v30, v29 offset0:32 offset1:98
	ds_write2_b32 v2, v32, v31 offset0:164 offset1:230
	v_add_u32_e32 v2, 0x1400, v11
	ds_write2_b32 v2, v34, v33 offset0:40 offset1:106
	ds_write2_b32 v2, v36, v35 offset0:172 offset1:238
	v_add_u32_e32 v2, 0x1800, v11
	ds_write2_b32 v2, v38, v37 offset0:48 offset1:114
	ds_write2_b32 v2, v40, v39 offset0:180 offset1:246
	v_add_u32_e32 v2, 0x1c00, v11
	ds_write2_b32 v2, v42, v41 offset0:56 offset1:122
	ds_write2_b32 v2, v44, v43 offset0:188 offset1:254
	s_waitcnt lgkmcnt(0)
	ds_read2_b32 v[2:3], v7 offset1:8
	ds_read2_b32 v[18:19], v7 offset0:33 offset1:41
	ds_read2_b32 v[20:21], v7 offset0:66 offset1:74
	ds_read2_b32 v[22:23], v7 offset0:99 offset1:107
	ds_read2_b32 v[24:25], v7 offset0:132 offset1:140
	s_waitcnt lgkmcnt(0)
	v_bfe_u32 v12, v2, 16, 1
	v_add3_u32 v2, v2, v12, s3
	v_bfe_u32 v12, v18, 16, 1
	v_lshrrev_b32_e32 v2, 16, v2
	v_add3_u32 v12, v18, v12, s3
	ds_read2_b32 v[26:27], v7 offset0:165 offset1:173
	v_and_or_b32 v12, v12, s33, v2
	v_bfe_u32 v2, v20, 16, 1
	v_add3_u32 v2, v20, v2, s3
	v_bfe_u32 v13, v22, 16, 1
	ds_read2_b32 v[28:29], v7 offset0:198 offset1:206
	v_lshrrev_b32_e32 v2, 16, v2
	v_add3_u32 v13, v22, v13, s3
	ds_read2_b32 v[30:31], v7 offset0:231 offset1:239
	v_and_or_b32 v13, v13, s33, v2
	v_bfe_u32 v2, v24, 16, 1
	v_add3_u32 v2, v24, v2, s3
	s_waitcnt lgkmcnt(2)
	v_bfe_u32 v14, v26, 16, 1
	v_lshrrev_b32_e32 v2, 16, v2
	v_add3_u32 v14, v26, v14, s3
	v_and_or_b32 v14, v14, s33, v2
	s_waitcnt lgkmcnt(1)
	v_bfe_u32 v2, v28, 16, 1
	s_ashr_i32 s11, s10, 31
	v_add3_u32 v2, v28, v2, s3
	s_waitcnt lgkmcnt(0)
	v_bfe_u32 v15, v30, 16, 1
	s_lshl_b64 s[10:11], s[10:11], 1
	v_lshrrev_b32_e32 v2, 16, v2
	v_add3_u32 v15, v30, v15, s3
	s_add_u32 s8, s8, s10
	v_and_or_b32 v15, v15, s33, v2
	v_or_b32_e32 v2, s7, v6
	s_addc_u32 s9, s9, s11
	v_mul_hi_i32_i24_e32 v33, s6, v2
	v_mul_i32_i24_e32 v32, s6, v2
	v_bfe_u32 v2, v3, 16, 1
	v_lshl_add_u64 v[16:17], s[8:9], 0, v[0:1]
	v_add3_u32 v2, v3, v2, s3
	v_bfe_u32 v3, v19, 16, 1
	v_lshl_add_u64 v[32:33], v[32:33], 1, v[16:17]
	v_lshrrev_b32_e32 v2, 16, v2
	v_add3_u32 v3, v19, v3, s3
	global_store_dwordx4 v[32:33], v[12:15], off sc1
	ds_read2_b32 v[18:19], v7 offset0:16 offset1:24
	s_add_i32 s78, s78, s79
	v_and_or_b32 v12, v3, s33, v2
	v_bfe_u32 v2, v21, 16, 1
	v_add3_u32 v2, v21, v2, s3
	v_bfe_u32 v3, v23, 16, 1
	v_lshrrev_b32_e32 v2, 16, v2
	v_add3_u32 v3, v23, v3, s3
	v_and_or_b32 v13, v3, s33, v2
	v_bfe_u32 v2, v25, 16, 1
	v_add3_u32 v2, v25, v2, s3
	v_bfe_u32 v3, v27, 16, 1
	v_lshrrev_b32_e32 v2, 16, v2
	v_add3_u32 v3, v27, v3, s3
	v_and_or_b32 v14, v3, s33, v2
	v_bfe_u32 v2, v29, 16, 1
	v_add3_u32 v2, v29, v2, s3
	v_bfe_u32 v3, v31, 16, 1
	v_lshrrev_b32_e32 v2, 16, v2
	v_add3_u32 v3, v31, v3, s3
	v_and_or_b32 v15, v3, s33, v2
	v_or_b32_e32 v2, s7, v8
	v_mul_hi_i32_i24_e32 v3, s6, v2
	v_mul_i32_i24_e32 v2, s6, v2
	v_lshl_add_u64 v[2:3], v[2:3], 1, v[16:17]
	global_store_dwordx4 v[2:3], v[12:15], off sc1
	ds_read2_b32 v[2:3], v7 offset0:49 offset1:57
	ds_read2_b32 v[20:21], v7 offset0:82 offset1:90
	ds_read2_b32 v[22:23], v7 offset0:115 offset1:123
	s_waitcnt lgkmcnt(3)
	v_bfe_u32 v12, v18, 16, 1
	v_add3_u32 v12, v18, v12, s3
	s_waitcnt lgkmcnt(2)
	v_bfe_u32 v13, v2, 16, 1
	ds_read2_b32 v[24:25], v7 offset0:148 offset1:156
	v_lshrrev_b32_e32 v12, 16, v12
	v_add3_u32 v2, v2, v13, s3
	ds_read2_b32 v[26:27], v7 offset0:181 offset1:189
	v_and_or_b32 v12, v2, s33, v12
	s_waitcnt lgkmcnt(3)
	v_bfe_u32 v2, v20, 16, 1
	v_add3_u32 v2, v20, v2, s3
	s_waitcnt lgkmcnt(2)
	v_bfe_u32 v13, v22, 16, 1
	ds_read2_b32 v[28:29], v7 offset0:214 offset1:222
	v_lshrrev_b32_e32 v2, 16, v2
	v_add3_u32 v13, v22, v13, s3
	ds_read2_b32 v[30:31], v7 offset0:247 offset1:255
	v_and_or_b32 v13, v13, s33, v2
	s_waitcnt lgkmcnt(3)
	v_bfe_u32 v2, v24, 16, 1
	v_add3_u32 v2, v24, v2, s3
	s_waitcnt lgkmcnt(2)
	v_bfe_u32 v14, v26, 16, 1
	v_lshrrev_b32_e32 v2, 16, v2
	v_add3_u32 v14, v26, v14, s3
	v_and_or_b32 v14, v14, s33, v2
	s_waitcnt lgkmcnt(1)
	v_bfe_u32 v2, v28, 16, 1
	v_add3_u32 v2, v28, v2, s3
	s_waitcnt lgkmcnt(0)
	v_bfe_u32 v15, v30, 16, 1
	v_lshrrev_b32_e32 v2, 16, v2
	v_add3_u32 v15, v30, v15, s3
	v_and_or_b32 v15, v15, s33, v2
	v_or_b32_e32 v2, s7, v9
	v_mul_hi_i32_i24_e32 v33, s6, v2
	v_mul_i32_i24_e32 v32, s6, v2
	v_lshl_add_u64 v[32:33], v[32:33], 1, v[16:17]
	v_bfe_u32 v2, v19, 16, 1
	global_store_dwordx4 v[32:33], v[12:15], off sc1
	v_add3_u32 v2, v19, v2, s3
	v_lshrrev_b32_e32 v2, 16, v2
	v_bfe_u32 v12, v3, 16, 1
	v_add3_u32 v3, v3, v12, s3
	v_and_or_b32 v12, v3, s33, v2
	v_bfe_u32 v2, v21, 16, 1
	v_add3_u32 v2, v21, v2, s3
	v_bfe_u32 v3, v23, 16, 1
	v_lshrrev_b32_e32 v2, 16, v2
	v_add3_u32 v3, v23, v3, s3
	v_and_or_b32 v13, v3, s33, v2
	v_bfe_u32 v2, v25, 16, 1
	v_add3_u32 v2, v25, v2, s3
	v_bfe_u32 v3, v27, 16, 1
	v_lshrrev_b32_e32 v2, 16, v2
	v_add3_u32 v3, v27, v3, s3
	v_and_or_b32 v14, v3, s33, v2
	v_bfe_u32 v2, v29, 16, 1
	v_add3_u32 v2, v29, v2, s3
	v_bfe_u32 v3, v31, 16, 1
	v_lshrrev_b32_e32 v2, 16, v2
	v_add3_u32 v3, v31, v3, s3
	v_and_or_b32 v15, v3, s33, v2
	v_or_b32_e32 v2, s7, v10
	v_mul_hi_i32_i24_e32 v3, s6, v2
	v_mul_i32_i24_e32 v2, s6, v2
	v_lshl_add_u64 v[2:3], v[2:3], 1, v[16:17]
	global_store_dwordx4 v[2:3], v[12:15], off sc1
	s_waitcnt lgkmcnt(0)
	s_mov_b64 s[10:11], 0

.LBB0_1576:
	s_mov_b32 s9, 0x2aaaaaab
	v_mul_hi_i32 v6, v0, s9
	v_lshrrev_b32_e32 v7, 31, v6
	v_ashrrev_i32_e32 v6, 12, v6
	v_add_u32_e32 v6, v6, v7
	v_mul_i32_i24_e32 v7, 0x6000, v6
	v_mul_i32_i24_e32 v6, 0x500, v6
	v_sub_u32_e32 v8, v0, v7
	v_ashrrev_i32_e32 v7, 31, v6
	v_lshlrev_b64 v[6:7], 11, v[6:7]
	s_mov_b32 s10, 0xbfff
	v_add_u32_e32 v0, s8, v0
	v_ashrrev_i32_e32 v9, 31, v8
	v_lshl_add_u64 v[6:7], s[46:47], 0, v[6:7]
	v_cmp_lt_i32_e32 vcc, s10, v0
	v_lshl_add_u64 v[6:7], v[8:9], 4, v[6:7]
	s_or_b64 s[6:7], vcc, s[6:7]
	v_add_co_u32_e32 v6, vcc, 0x5720000, v6
	s_nop 1
	v_addc_co_u32_e32 v7, vcc, 0, v7, vcc
	global_store_dwordx4 v[6:7], v[2:5], off sc1
	s_andn2_b64 exec, exec, s[6:7]
	s_cbranch_execnz .LBB0_1576
